# hot loop headers (4 GEMM main loops, DeltaNet chunk loop, attention k-loop tail) aligned to 64 bytes with s_nop fill
# baseline (speedup 1.0000x reference)
.LBB0_282:
	v_mov_b32_e32 v129, v131
	v_lshl_add_u64 v[0:1], s[6:7], 0, v[130:131]
	v_lshl_add_u64 v[2:3], s[6:7], 0, v[128:129]
	v_readfirstlane_b32 s6, v154
	v_lshl_add_u64 v[0:1], v[0:1], 0, s[80:81]
	s_mov_b32 m0, s6
	v_readfirstlane_b32 s6, v155
	v_lshl_add_u64 v[4:5], s[8:9], 0, v[130:131]
	s_waitcnt vmcnt(4)
	s_barrier
	global_load_lds_dwordx4 v[0:1], off
	v_lshl_add_u64 v[0:1], v[2:3], 0, s[80:81]
	s_mov_b32 m0, s6
	v_readfirstlane_b32 s6, v156
	v_lshl_add_u64 v[6:7], s[8:9], 0, v[128:129]
	global_load_lds_dwordx4 v[0:1], off
	v_lshl_add_u64 v[0:1], v[4:5], 0, s[80:81]
	s_mov_b32 m0, s6
	v_readfirstlane_b32 s6, v157
	v_lshl_add_u64 v[8:9], s[10:11], 0, v[130:131]
	global_load_lds_dwordx4 v[0:1], off
	v_lshl_add_u64 v[0:1], v[6:7], 0, s[80:81]
	s_mov_b32 m0, s6
	v_readfirstlane_b32 s6, v158
	v_lshl_add_u64 v[10:11], s[10:11], 0, v[128:129]
	global_load_lds_dwordx4 v[0:1], off
	v_lshl_add_u64 v[0:1], v[8:9], 0, s[80:81]
	s_mov_b32 m0, s6
	v_readfirstlane_b32 s6, v159
	global_load_lds_dwordx4 v[0:1], off
	v_lshl_add_u64 v[0:1], v[10:11], 0, s[80:81]
	s_mov_b32 m0, s6
	v_lshl_add_u64 v[134:135], s[12:13], 0, v[130:131]
	global_load_lds_dwordx4 v[0:1], off
	s_waitcnt vmcnt(6)
	v_mov_b32_e32 v0, 0
	v_lshl_add_u64 v[132:133], s[12:13], 0, v[128:129]
	v_lshl_add_u64 v[136:137], s[0:1], 0, v[130:131]
	v_lshl_add_u64 v[138:139], s[0:1], 0, v[128:129]
	v_lshl_add_u64 v[140:141], s[4:5], 0, v[130:131]
	v_lshl_add_u64 v[142:143], s[4:5], 0, v[128:129]
	s_mov_b32 s4, -2
	s_mov_b64 s[0:1], s[28:29]
	v_mov_b32_e32 v1, v0
	v_mov_b32_e32 v2, v0
	v_mov_b32_e32 v3, v0
	v_mov_b32_e32 v4, v0
	v_mov_b32_e32 v5, v0
	v_mov_b32_e32 v6, v0
	v_mov_b32_e32 v7, v0
	v_mov_b32_e32 v8, v0
	v_mov_b32_e32 v9, v0
	v_mov_b32_e32 v10, v0
	v_mov_b32_e32 v11, v0
	v_mov_b32_e32 v12, v0
	v_mov_b32_e32 v13, v0
	v_mov_b32_e32 v14, v0
	v_mov_b32_e32 v15, v0
	v_mov_b32_e32 v16, v0
	v_mov_b32_e32 v17, v0
	v_mov_b32_e32 v18, v0
	v_mov_b32_e32 v19, v0
	v_mov_b32_e32 v20, v0
	v_mov_b32_e32 v21, v0
	v_mov_b32_e32 v22, v0
	v_mov_b32_e32 v23, v0
	v_mov_b32_e32 v24, v0
	v_mov_b32_e32 v25, v0
	v_mov_b32_e32 v26, v0
	v_mov_b32_e32 v27, v0
	v_mov_b32_e32 v28, v0
	v_mov_b32_e32 v29, v0
	v_mov_b32_e32 v30, v0
	v_mov_b32_e32 v31, v0
	v_mov_b32_e32 v32, v0
	v_mov_b32_e32 v33, v0
	v_mov_b32_e32 v34, v0
	v_mov_b32_e32 v35, v0
	v_mov_b32_e32 v36, v0
	v_mov_b32_e32 v37, v0
	v_mov_b32_e32 v38, v0
	v_mov_b32_e32 v39, v0
	v_mov_b32_e32 v40, v0
	v_mov_b32_e32 v41, v0
	v_mov_b32_e32 v42, v0
	v_mov_b32_e32 v43, v0
	v_mov_b32_e32 v44, v0
	v_mov_b32_e32 v45, v0
	v_mov_b32_e32 v46, v0
	v_mov_b32_e32 v47, v0
	v_mov_b32_e32 v48, v0
	v_mov_b32_e32 v49, v0
	v_mov_b32_e32 v50, v0
	v_mov_b32_e32 v51, v0
	v_mov_b32_e32 v52, v0
	v_mov_b32_e32 v53, v0
	v_mov_b32_e32 v54, v0
	v_mov_b32_e32 v55, v0
	v_mov_b32_e32 v56, v0
	v_mov_b32_e32 v57, v0
	v_mov_b32_e32 v58, v0
	v_mov_b32_e32 v59, v0
	v_mov_b32_e32 v60, v0
	v_mov_b32_e32 v61, v0
	v_mov_b32_e32 v62, v0
	v_mov_b32_e32 v63, v0
	v_mov_b32_e32 v64, v0
	v_mov_b32_e32 v65, v0
	v_mov_b32_e32 v66, v0
	v_mov_b32_e32 v67, v0
	v_mov_b32_e32 v68, v0
	v_mov_b32_e32 v69, v0
	v_mov_b32_e32 v70, v0
	v_mov_b32_e32 v71, v0
	v_mov_b32_e32 v72, v0
	v_mov_b32_e32 v73, v0
	v_mov_b32_e32 v74, v0
	v_mov_b32_e32 v75, v0
	v_mov_b32_e32 v76, v0
	v_mov_b32_e32 v77, v0
	v_mov_b32_e32 v78, v0
	v_mov_b32_e32 v79, v0
	v_mov_b32_e32 v80, v0
	v_mov_b32_e32 v81, v0
	v_mov_b32_e32 v82, v0
	v_mov_b32_e32 v83, v0
	v_mov_b32_e32 v84, v0
	v_mov_b32_e32 v85, v0
	v_mov_b32_e32 v86, v0
	v_mov_b32_e32 v87, v0
	v_mov_b32_e32 v88, v0
	v_mov_b32_e32 v89, v0
	v_mov_b32_e32 v90, v0
	v_mov_b32_e32 v91, v0
	v_mov_b32_e32 v92, v0
	v_mov_b32_e32 v93, v0
	v_mov_b32_e32 v94, v0
	v_mov_b32_e32 v95, v0
	v_mov_b32_e32 v96, v0
	v_mov_b32_e32 v97, v0
	v_mov_b32_e32 v98, v0
	v_mov_b32_e32 v99, v0
	v_mov_b32_e32 v100, v0
	v_mov_b32_e32 v101, v0
	v_mov_b32_e32 v102, v0
	v_mov_b32_e32 v103, v0
	v_mov_b32_e32 v104, v0
	v_mov_b32_e32 v105, v0
	v_mov_b32_e32 v106, v0
	v_mov_b32_e32 v107, v0
	v_mov_b32_e32 v108, v0
	v_mov_b32_e32 v109, v0
	v_mov_b32_e32 v110, v0
	v_mov_b32_e32 v111, v0
	v_mov_b32_e32 v112, v0
	v_mov_b32_e32 v113, v0
	v_mov_b32_e32 v114, v0
	v_mov_b32_e32 v115, v0
	v_mov_b32_e32 v116, v0
	v_mov_b32_e32 v117, v0
	v_mov_b32_e32 v118, v0
	v_mov_b32_e32 v119, v0
	v_mov_b32_e32 v120, v0
	v_mov_b32_e32 v121, v0
	v_mov_b32_e32 v122, v0
	v_mov_b32_e32 v123, v0
	v_mov_b32_e32 v124, v0
	v_mov_b32_e32 v125, v0
	v_mov_b32_e32 v126, v0
	v_mov_b32_e32 v127, v0
	s_barrier
	.p2alignl 6, 3212836864

.LBB0_644:
	s_or_b64 exec, exec, s[0:1]
	v_add_u32_e32 v111, -1, v111
	v_cmp_eq_u32_e32 vcc, -1, v111
	s_or_b64 s[16:17], vcc, s[16:17]
	s_waitcnt lgkmcnt(0)
	s_barrier
	s_andn2_b64 exec, exec, s[16:17]
	s_cbranch_execz .LBB0_708
	.p2alignl 6, 3212836864

.LBB0_716:
	s_or_b64 exec, exec, s[6:7]
	v_ashrrev_i32_e32 v32, 4, v3
	v_add_u32_e32 v4, v4, v32
	v_ashrrev_i32_e32 v5, 31, v4
	v_mov_b32_e32 v1, v2
	v_lshlrev_b64 v[26:27], 11, v[4:5]
	v_lshlrev_b32_e32 v6, 3, v3
	v_lshlrev_b64 v[24:25], 1, v[0:1]
	v_lshl_add_u64 v[4:5], s[74:75], 0, v[26:27]
	v_and_b32_e32 v7, 0x78, v6
	v_lshl_add_u64 v[4:5], v[4:5], 0, v[24:25]
	v_lshlrev_b32_e32 v102, 1, v7
	v_mov_b32_e32 v103, v2
	v_ashrrev_i32_e32 v34, 3, v3
	v_lshl_add_u64 v[8:9], v[4:5], 0, v[102:103]
	v_mad_i64_i32 v[4:5], s[6:7], v23, v34, 0
	v_and_b32_e32 v6, 56, v6
	v_lshl_add_u64 v[4:5], v[4:5], 1, v[20:21]
	v_lshlrev_b32_e32 v104, 1, v6
	v_mov_b32_e32 v105, v2
	s_mov_b32 s6, 0x10000
	v_lshl_add_u64 v[16:17], v[4:5], 0, v[104:105]
	global_load_dwordx4 v[4:7], v[8:9], off
	v_add_co_u32_e32 v8, vcc, s6, v8
	s_ashr_i32 s6, s8, 2
	s_waitcnt vmcnt(25)
	v_bfi_b32 v38, -16, s6, v3
	v_mov_b64_e32 v[28:29], s[16:17]
	v_and_b32_e32 v37, 7, v3
	s_movk_i32 s7, 0x88
	s_waitcnt vmcnt(24)
	v_lshlrev_b32_e32 v41, 1, v34
	v_add_u32_e32 v100, v38, v22
	v_bfe_u32 v35, v3, 4, 2
	v_mov_b32_e32 v33, v2
	v_mul_lo_u32 v39, v32, s7
	v_lshlrev_b32_e32 v32, 4, v37
	v_add_u32_e32 v22, 0x80, v41
	v_mad_i64_i32 v[28:29], s[6:7], v100, s20, v[28:29]
	v_addc_co_u32_e32 v9, vcc, 0, v9, vcc
	v_lshlrev_b32_e32 v18, 7, v23
	v_mov_b32_e32 v19, v2
	v_and_b32_e32 v36, 15, v3
	v_mov_b32_e32 v31, v2
	v_lshrrev_b32_e32 v103, 6, v23
	v_lshl_add_u64 v[20:21], v[20:21], 0, s[52:53]
	s_waitcnt vmcnt(23)
	v_lshlrev_b32_e32 v44, 3, v35
	v_lshlrev_b32_e32 v30, 4, v35
	v_mul_lo_u32 v40, v34, s23
	v_lshlrev_b32_e32 v3, 2, v35
	v_mad_i64_i32 v[34:35], s[6:7], v41, v23, v[32:33]
	v_mad_i64_i32 v[22:23], s[6:7], v22, v23, v[32:33]
	v_lshl_add_u64 v[28:29], v[28:29], 0, v[24:25]
	global_load_dwordx4 v[8:11], v[8:9], off
	s_nop 0
	global_load_dwordx4 v[12:15], v[16:17], off
	v_lshl_add_u64 v[16:17], v[16:17], 0, v[18:19]
	v_lshl_add_u64 v[106:107], v[20:21], 0, v[34:35]
	v_lshl_add_u64 v[108:109], v[20:21], 0, v[22:23]
	v_lshl_add_u64 v[20:21], v[28:29], 0, v[30:31]
	global_load_dwordx4 v[16:19], v[16:17], off
	v_mul_u32_u24_e32 v105, 0x110, v36
	v_mul_u32_u24_e32 v115, 0x90, v36
	v_mad_u32_u24 v152, v36, s24, v146
	v_mad_u32_u24 v153, v36, s24, v147
	v_mad_u32_u24 v154, v36, s24, v151
	v_lshlrev_b32_e32 v155, 1, v39
	v_lshlrev_b32_e32 v156, 1, v40
	v_lshl_or_b32 v26, v36, 4, v26
	global_load_dwordx4 v[36:39], v[20:21], off
	global_load_dwordx4 v[40:43], v[20:21], off offset:64
	global_load_dwordx4 v[48:51], v[20:21], off offset:128
	global_load_dwordx4 v[52:55], v[20:21], off offset:192
	v_add3_u32 v45, 16, v155, v102
	v_add3_u32 v46, 16, v156, v104
	v_lshl_add_u64 v[22:23], v[26:27], 0, v[24:25]
	v_mov_b32_e32 v24, 0
	s_mov_b32 s12, 1
	v_ashrrev_i32_e32 v101, 31, v100
	s_waitcnt vmcnt(26)
	v_lshl_add_u64 v[110:111], s[72:73], 0, v[22:23]
	s_barrier
	v_sub_u32_e32 v157, 0, v103
	v_mov_b32_e32 v116, 0xf149f2ca
	s_mov_b64 s[8:9], 0
	v_lshlrev_b32_e32 v158, 1, v44
	v_mov_b32_e32 v117, 0xf149f2ca
	v_mov_b32_e32 v25, v24
	v_mov_b32_e32 v26, v24
	v_mov_b32_e32 v27, v24
	v_mov_b32_e32 v56, v24
	s_waitcnt vmcnt(7)
	ds_write_b128 v45, v[4:7]
	s_waitcnt vmcnt(6)
	ds_write_b128 v45, v[8:11] offset:8704
	s_waitcnt vmcnt(5)
	ds_write_b128 v46, v[12:15] offset:17408
	s_waitcnt vmcnt(4)
	ds_write_b128 v46, v[16:19] offset:26624
	v_mov_b32_e32 v57, v24
	v_mov_b32_e32 v58, v24
	v_mov_b32_e32 v59, v24
	v_mov_b32_e32 v68, v24
	v_mov_b32_e32 v69, v24
	v_mov_b32_e32 v70, v24
	v_mov_b32_e32 v71, v24
	v_mov_b32_e32 v80, v24
	v_mov_b32_e32 v81, v24
	v_mov_b32_e32 v82, v24
	v_mov_b32_e32 v83, v24
	v_mov_b32_e32 v84, v24
	v_mov_b32_e32 v85, v24
	v_mov_b32_e32 v86, v24
	v_mov_b32_e32 v87, v24
	v_mov_b32_e32 v20, v24
	v_mov_b32_e32 v21, v24
	v_mov_b32_e32 v22, v24
	v_mov_b32_e32 v23, v24
	v_mov_b32_e32 v28, v24
	v_mov_b32_e32 v29, v24
	v_mov_b32_e32 v30, v24
	v_mov_b32_e32 v31, v24
	v_mov_b32_e32 v60, v24
	v_mov_b32_e32 v61, v24
	v_mov_b32_e32 v62, v24
	v_mov_b32_e32 v63, v24
	v_mov_b32_e32 v72, v24
	v_mov_b32_e32 v73, v24
	v_mov_b32_e32 v74, v24
	v_mov_b32_e32 v75, v24
	v_mov_b32_e32 v76, v24
	v_mov_b32_e32 v77, v24
	v_mov_b32_e32 v78, v24
	v_mov_b32_e32 v79, v24
	v_mov_b32_e32 v92, v24
	v_mov_b32_e32 v93, v24
	v_mov_b32_e32 v94, v24
	v_mov_b32_e32 v95, v24
	v_mov_b32_e32 v96, v24
	v_mov_b32_e32 v97, v24
	v_mov_b32_e32 v98, v24
	v_mov_b32_e32 v99, v24
	v_mov_b32_e32 v64, v24
	v_mov_b32_e32 v65, v24
	v_mov_b32_e32 v66, v24
	v_mov_b32_e32 v67, v24
	v_mov_b32_e32 v44, v24
	v_mov_b32_e32 v45, v24
	v_mov_b32_e32 v46, v24
	v_mov_b32_e32 v47, v24
	v_mov_b32_e32 v32, v24
	v_mov_b32_e32 v33, v24
	v_mov_b32_e32 v34, v24
	v_mov_b32_e32 v35, v24
	v_mov_b32_e32 v88, v24
	v_mov_b32_e32 v89, v24
	v_mov_b32_e32 v90, v24
	v_mov_b32_e32 v91, v24
	v_mov_b32_e32 v112, v24
	v_mov_b32_e32 v113, v24
	s_waitcnt vmcnt(0) lgkmcnt(0)
	s_barrier
	s_branch .LBB0_718
	.p2alignl 6, 3212836864

.LBB0_920:
	v_mov_b32_e32 v131, v133
	v_lshl_add_u64 v[0:1], s[24:25], 0, v[130:131]
	v_mov_b32_e32 v129, v133
	v_readfirstlane_b32 s21, v156
	v_lshl_add_u64 v[2:3], s[24:25], 0, v[128:129]
	v_lshl_add_u64 v[0:1], v[0:1], 0, s[8:9]
	s_mov_b32 m0, s21
	v_readfirstlane_b32 s21, v157
	v_lshl_add_u64 v[4:5], s[26:27], 0, v[130:131]
	s_waitcnt vmcnt(4)
	s_barrier
	global_load_lds_dwordx4 v[0:1], off
	v_lshl_add_u64 v[0:1], v[2:3], 0, s[8:9]
	s_mov_b32 m0, s21
	v_readfirstlane_b32 s21, v158
	v_lshl_add_u64 v[6:7], s[26:27], 0, v[128:129]
	global_load_lds_dwordx4 v[0:1], off
	v_lshl_add_u64 v[0:1], v[4:5], 0, s[8:9]
	s_mov_b32 m0, s21
	v_readfirstlane_b32 s21, v159
	v_lshl_add_u64 v[8:9], s[54:55], 0, v[130:131]
	global_load_lds_dwordx4 v[0:1], off
	v_lshl_add_u64 v[0:1], v[6:7], 0, s[8:9]
	s_mov_b32 m0, s21
	v_readfirstlane_b32 s21, v160
	v_lshl_add_u64 v[10:11], s[54:55], 0, v[128:129]
	global_load_lds_dwordx4 v[0:1], off
	v_lshl_add_u64 v[0:1], v[8:9], 0, s[8:9]
	s_mov_b32 m0, s21
	v_readfirstlane_b32 s21, v161
	global_load_lds_dwordx4 v[0:1], off
	v_lshl_add_u64 v[0:1], v[10:11], 0, s[8:9]
	s_mov_b32 m0, s21
	v_lshl_add_u64 v[136:137], s[56:57], 0, v[130:131]
	global_load_lds_dwordx4 v[0:1], off
	s_waitcnt vmcnt(6)
	v_mov_b32_e32 v0, 0
	v_lshl_add_u64 v[134:135], s[56:57], 0, v[128:129]
	v_lshl_add_u64 v[138:139], s[18:19], 0, v[130:131]
	v_lshl_add_u64 v[140:141], s[18:19], 0, v[128:129]
	v_lshl_add_u64 v[142:143], s[22:23], 0, v[130:131]
	v_lshl_add_u64 v[144:145], s[22:23], 0, v[128:129]
	s_mov_b32 s18, -2
	s_mov_b64 s[22:23], s[28:29]
	v_mov_b32_e32 v1, v0
	v_mov_b32_e32 v2, v0
	v_mov_b32_e32 v3, v0
	v_mov_b32_e32 v4, v0
	v_mov_b32_e32 v5, v0
	v_mov_b32_e32 v6, v0
	v_mov_b32_e32 v7, v0
	v_mov_b32_e32 v8, v0
	v_mov_b32_e32 v9, v0
	v_mov_b32_e32 v10, v0
	v_mov_b32_e32 v11, v0
	v_mov_b32_e32 v12, v0
	v_mov_b32_e32 v13, v0
	v_mov_b32_e32 v14, v0
	v_mov_b32_e32 v15, v0
	v_mov_b32_e32 v16, v0
	v_mov_b32_e32 v17, v0
	v_mov_b32_e32 v18, v0
	v_mov_b32_e32 v19, v0
	v_mov_b32_e32 v20, v0
	v_mov_b32_e32 v21, v0
	v_mov_b32_e32 v22, v0
	v_mov_b32_e32 v23, v0
	v_mov_b32_e32 v24, v0
	v_mov_b32_e32 v25, v0
	v_mov_b32_e32 v26, v0
	v_mov_b32_e32 v27, v0
	v_mov_b32_e32 v28, v0
	v_mov_b32_e32 v29, v0
	v_mov_b32_e32 v30, v0
	v_mov_b32_e32 v31, v0
	v_mov_b32_e32 v32, v0
	v_mov_b32_e32 v33, v0
	v_mov_b32_e32 v34, v0
	v_mov_b32_e32 v35, v0
	v_mov_b32_e32 v36, v0
	v_mov_b32_e32 v37, v0
	v_mov_b32_e32 v38, v0
	v_mov_b32_e32 v39, v0
	v_mov_b32_e32 v40, v0
	v_mov_b32_e32 v41, v0
	v_mov_b32_e32 v42, v0
	v_mov_b32_e32 v43, v0
	v_mov_b32_e32 v44, v0
	v_mov_b32_e32 v45, v0
	v_mov_b32_e32 v46, v0
	v_mov_b32_e32 v47, v0
	v_mov_b32_e32 v48, v0
	v_mov_b32_e32 v49, v0
	v_mov_b32_e32 v50, v0
	v_mov_b32_e32 v51, v0
	v_mov_b32_e32 v52, v0
	v_mov_b32_e32 v53, v0
	v_mov_b32_e32 v54, v0
	v_mov_b32_e32 v55, v0
	v_mov_b32_e32 v56, v0
	v_mov_b32_e32 v57, v0
	v_mov_b32_e32 v58, v0
	v_mov_b32_e32 v59, v0
	v_mov_b32_e32 v60, v0
	v_mov_b32_e32 v61, v0
	v_mov_b32_e32 v62, v0
	v_mov_b32_e32 v63, v0
	v_mov_b32_e32 v64, v0
	v_mov_b32_e32 v65, v0
	v_mov_b32_e32 v66, v0
	v_mov_b32_e32 v67, v0
	v_mov_b32_e32 v68, v0
	v_mov_b32_e32 v69, v0
	v_mov_b32_e32 v70, v0
	v_mov_b32_e32 v71, v0
	v_mov_b32_e32 v72, v0
	v_mov_b32_e32 v73, v0
	v_mov_b32_e32 v74, v0
	v_mov_b32_e32 v75, v0
	v_mov_b32_e32 v76, v0
	v_mov_b32_e32 v77, v0
	v_mov_b32_e32 v78, v0
	v_mov_b32_e32 v79, v0
	v_mov_b32_e32 v80, v0
	v_mov_b32_e32 v81, v0
	v_mov_b32_e32 v82, v0
	v_mov_b32_e32 v83, v0
	v_mov_b32_e32 v84, v0
	v_mov_b32_e32 v85, v0
	v_mov_b32_e32 v86, v0
	v_mov_b32_e32 v87, v0
	v_mov_b32_e32 v88, v0
	v_mov_b32_e32 v89, v0
	v_mov_b32_e32 v90, v0
	v_mov_b32_e32 v91, v0
	v_mov_b32_e32 v92, v0
	v_mov_b32_e32 v93, v0
	v_mov_b32_e32 v94, v0
	v_mov_b32_e32 v95, v0
	v_mov_b32_e32 v96, v0
	v_mov_b32_e32 v97, v0
	v_mov_b32_e32 v98, v0
	v_mov_b32_e32 v99, v0
	v_mov_b32_e32 v100, v0
	v_mov_b32_e32 v101, v0
	v_mov_b32_e32 v102, v0
	v_mov_b32_e32 v103, v0
	v_mov_b32_e32 v104, v0
	v_mov_b32_e32 v105, v0
	v_mov_b32_e32 v106, v0
	v_mov_b32_e32 v107, v0
	v_mov_b32_e32 v108, v0
	v_mov_b32_e32 v109, v0
	v_mov_b32_e32 v110, v0
	v_mov_b32_e32 v111, v0
	v_mov_b32_e32 v112, v0
	v_mov_b32_e32 v113, v0
	v_mov_b32_e32 v114, v0
	v_mov_b32_e32 v115, v0
	v_mov_b32_e32 v116, v0
	v_mov_b32_e32 v117, v0
	v_mov_b32_e32 v118, v0
	v_mov_b32_e32 v119, v0
	v_mov_b32_e32 v120, v0
	v_mov_b32_e32 v121, v0
	v_mov_b32_e32 v122, v0
	v_mov_b32_e32 v123, v0
	v_mov_b32_e32 v124, v0
	v_mov_b32_e32 v125, v0
	v_mov_b32_e32 v126, v0
	v_mov_b32_e32 v127, v0
	s_barrier
	.p2alignl 6, 3212836864

.LBB0_1122:
	v_mov_b32_e32 v227, v229
	v_lshl_add_u64 v[0:1], s[22:23], 0, v[228:229]
	v_lshl_add_u64 v[2:3], s[22:23], 0, v[226:227]
	v_readfirstlane_b32 s22, v240
	v_lshl_add_u64 v[0:1], v[0:1], 0, s[16:17]
	s_mov_b32 m0, s22
	v_readfirstlane_b32 s22, v241
	v_lshl_add_u64 v[4:5], s[24:25], 0, v[228:229]
	s_waitcnt vmcnt(4)
	s_barrier
	global_load_lds_dwordx4 v[0:1], off
	v_lshl_add_u64 v[0:1], v[2:3], 0, s[16:17]
	s_mov_b32 m0, s22
	v_readfirstlane_b32 s22, v242
	v_lshl_add_u64 v[6:7], s[24:25], 0, v[226:227]
	global_load_lds_dwordx4 v[0:1], off
	v_lshl_add_u64 v[0:1], v[4:5], 0, s[16:17]
	s_mov_b32 m0, s22
	v_readfirstlane_b32 s22, v243
	v_lshl_add_u64 v[8:9], s[26:27], 0, v[228:229]
	global_load_lds_dwordx4 v[0:1], off
	v_lshl_add_u64 v[0:1], v[6:7], 0, s[16:17]
	s_mov_b32 m0, s22
	v_readfirstlane_b32 s22, v244
	v_lshl_add_u64 v[10:11], s[26:27], 0, v[226:227]
	global_load_lds_dwordx4 v[0:1], off
	v_lshl_add_u64 v[0:1], v[8:9], 0, s[16:17]
	s_mov_b32 m0, s22
	v_readfirstlane_b32 s22, v245
	global_load_lds_dwordx4 v[0:1], off
	v_lshl_add_u64 v[0:1], v[10:11], 0, s[16:17]
	s_mov_b32 m0, s22
	s_lshl_b32 s24, s78, 11
	global_load_lds_dwordx4 v[0:1], off
	v_lshl_add_u64 v[192:193], s[4:5], 0, v[228:229]
	v_lshl_add_u64 v[194:195], s[4:5], 0, v[226:227]
	s_or_b32 s4, s76, s24
	s_lshl_b32 s25, s79, 8
	s_add_i32 s4, s4, s25
	s_waitcnt vmcnt(6)
	s_ashr_i32 s5, s4, 31
	v_mov_b32_e32 v2, v229
	v_mov_b32_e32 v3, v229
	s_lshl_b64 s[4:5], s[4:5], 12
	v_mov_b32_e32 v0, v229
	v_mov_b32_e32 v1, v229
	v_mov_b32_e32 v64, 0
	v_mov_b64_e32 v[6:7], v[2:3]
	v_mov_b64_e32 v[10:11], v[2:3]
	v_mov_b64_e32 v[14:15], v[2:3]
	v_mov_b64_e32 v[26:27], v[2:3]
	v_mov_b64_e32 v[30:31], v[2:3]
	v_mov_b64_e32 v[42:43], v[2:3]
	v_mov_b64_e32 v[46:47], v[2:3]
	v_mov_b64_e32 v[18:19], v[2:3]
	v_mov_b64_e32 v[22:23], v[2:3]
	v_mov_b64_e32 v[34:35], v[2:3]
	v_mov_b64_e32 v[38:39], v[2:3]
	v_mov_b64_e32 v[50:51], v[2:3]
	v_mov_b64_e32 v[54:55], v[2:3]
	v_mov_b64_e32 v[58:59], v[2:3]
	v_mov_b64_e32 v[62:63], v[2:3]
	v_lshl_add_u64 v[210:211], s[52:53], 0, v[228:229]
	v_lshl_add_u64 v[208:209], s[52:53], 0, v[226:227]
	v_lshl_add_u64 v[196:197], s[4:5], 0, v[228:229]
	v_lshl_add_u64 v[198:199], s[4:5], 0, v[226:227]
	v_lshl_add_u64 v[200:201], s[18:19], 0, v[228:229]
	v_lshl_add_u64 v[202:203], s[18:19], 0, v[226:227]
	s_mov_b32 s18, -2
	s_mov_b64 s[22:23], s[28:29]
	v_mov_b64_e32 v[4:5], v[0:1]
	v_mov_b64_e32 v[8:9], v[0:1]
	v_mov_b64_e32 v[12:13], v[0:1]
	v_mov_b64_e32 v[24:25], v[0:1]
	v_mov_b64_e32 v[28:29], v[0:1]
	v_mov_b64_e32 v[40:41], v[0:1]
	v_mov_b64_e32 v[44:45], v[0:1]
	v_mov_b64_e32 v[16:17], v[0:1]
	v_mov_b64_e32 v[20:21], v[0:1]
	v_mov_b64_e32 v[32:33], v[0:1]
	v_mov_b64_e32 v[36:37], v[0:1]
	v_mov_b64_e32 v[48:49], v[0:1]
	v_mov_b64_e32 v[52:53], v[0:1]
	v_mov_b64_e32 v[56:57], v[0:1]
	v_mov_b64_e32 v[60:61], v[0:1]
	v_mov_b32_e32 v65, v64
	v_mov_b32_e32 v66, v64
	v_mov_b32_e32 v67, v64
	v_mov_b32_e32 v68, v64
	v_mov_b32_e32 v69, v64
	v_mov_b32_e32 v70, v64
	v_mov_b32_e32 v71, v64
	v_mov_b32_e32 v72, v64
	v_mov_b32_e32 v73, v64
	v_mov_b32_e32 v74, v64
	v_mov_b32_e32 v75, v64
	v_mov_b32_e32 v76, v64
	v_mov_b32_e32 v77, v64
	v_mov_b32_e32 v78, v64
	v_mov_b32_e32 v79, v64
	v_mov_b32_e32 v80, v64
	v_mov_b32_e32 v81, v64
	v_mov_b32_e32 v82, v64
	v_mov_b32_e32 v83, v64
	v_mov_b32_e32 v84, v64
	v_mov_b32_e32 v85, v64
	v_mov_b32_e32 v86, v64
	v_mov_b32_e32 v87, v64
	v_mov_b32_e32 v88, v64
	v_mov_b32_e32 v89, v64
	v_mov_b32_e32 v90, v64
	v_mov_b32_e32 v91, v64
	v_mov_b32_e32 v92, v64
	v_mov_b32_e32 v93, v64
	v_mov_b32_e32 v94, v64
	v_mov_b32_e32 v95, v64
	v_mov_b32_e32 v96, v64
	v_mov_b32_e32 v97, v64
	v_mov_b32_e32 v98, v64
	v_mov_b32_e32 v99, v64
	v_mov_b32_e32 v100, v64
	v_mov_b32_e32 v101, v64
	v_mov_b32_e32 v102, v64
	v_mov_b32_e32 v103, v64
	v_mov_b32_e32 v104, v64
	v_mov_b32_e32 v105, v64
	v_mov_b32_e32 v106, v64
	v_mov_b32_e32 v107, v64
	v_mov_b32_e32 v108, v64
	v_mov_b32_e32 v109, v64
	v_mov_b32_e32 v110, v64
	v_mov_b32_e32 v111, v64
	v_mov_b32_e32 v112, v64
	v_mov_b32_e32 v113, v64
	v_mov_b32_e32 v114, v64
	v_mov_b32_e32 v115, v64
	v_mov_b32_e32 v116, v64
	v_mov_b32_e32 v117, v64
	v_mov_b32_e32 v118, v64
	v_mov_b32_e32 v119, v64
	v_mov_b32_e32 v120, v64
	v_mov_b32_e32 v121, v64
	v_mov_b32_e32 v122, v64
	v_mov_b32_e32 v123, v64
	v_mov_b32_e32 v124, v64
	v_mov_b32_e32 v125, v64
	v_mov_b32_e32 v126, v64
	v_mov_b32_e32 v127, v64
	s_barrier
	s_branch .LBB0_1124
	.p2alignl 6, 3212836864

.LBB0_1470:
	v_mov_b32_e32 v129, v131
	v_lshl_add_u64 v[0:1], s[42:43], 0, v[130:131]
	v_lshl_add_u64 v[4:5], s[44:45], 0, v[130:131]
	v_lshl_add_u64 v[6:7], s[44:45], 0, v[128:129]
	v_readfirstlane_b32 s44, v155
	v_lshl_add_u64 v[2:3], s[42:43], 0, v[128:129]
	v_lshl_add_u64 v[0:1], v[0:1], 0, s[8:9]
	s_mov_b32 m0, s44
	v_readfirstlane_b32 s44, v156
	s_waitcnt vmcnt(4)
	s_barrier
	global_load_lds_dwordx4 v[0:1], off
	v_lshl_add_u64 v[0:1], v[2:3], 0, s[8:9]
	s_mov_b32 m0, s44
	v_readfirstlane_b32 s44, v150
	global_load_lds_dwordx4 v[0:1], off
	v_lshl_add_u64 v[0:1], v[4:5], 0, s[8:9]
	s_mov_b32 m0, s44
	v_readfirstlane_b32 s44, v151
	s_add_u32 s42, s42, 0x160080
	global_load_lds_dwordx4 v[0:1], off
	v_lshl_add_u64 v[0:1], v[6:7], 0, s[8:9]
	s_mov_b32 m0, s44
	s_addc_u32 s43, s43, 0
	v_readfirstlane_b32 s44, v157
	global_load_lds_dwordx4 v[0:1], off
	v_lshl_add_u64 v[0:1], s[42:43], 0, v[130:131]
	s_mov_b32 m0, s44
	v_lshl_add_u64 v[132:133], s[18:19], 0, v[130:131]
	global_load_lds_dwordx4 v[0:1], off
	v_lshl_add_u64 v[0:1], s[42:43], 0, v[128:129]
	v_readfirstlane_b32 s42, v158
	s_mov_b32 m0, s42
	v_lshl_add_u64 v[134:135], s[18:19], 0, v[128:129]
	global_load_lds_dwordx4 v[0:1], off
	s_waitcnt vmcnt(6)
	v_mov_b32_e32 v0, 0
	v_lshl_add_u64 v[136:137], s[26:27], 0, v[130:131]
	v_lshl_add_u64 v[138:139], s[26:27], 0, v[128:129]
	s_mov_b32 s18, -2
	s_mov_b64 s[26:27], s[28:29]
	v_mov_b32_e32 v1, v0
	v_mov_b32_e32 v2, v0
	v_mov_b32_e32 v3, v0
	v_mov_b32_e32 v4, v0
	v_mov_b32_e32 v5, v0
	v_mov_b32_e32 v6, v0
	v_mov_b32_e32 v7, v0
	v_mov_b32_e32 v8, v0
	v_mov_b32_e32 v9, v0
	v_mov_b32_e32 v10, v0
	v_mov_b32_e32 v11, v0
	v_mov_b32_e32 v12, v0
	v_mov_b32_e32 v13, v0
	v_mov_b32_e32 v14, v0
	v_mov_b32_e32 v15, v0
	v_mov_b32_e32 v16, v0
	v_mov_b32_e32 v17, v0
	v_mov_b32_e32 v18, v0
	v_mov_b32_e32 v19, v0
	v_mov_b32_e32 v20, v0
	v_mov_b32_e32 v21, v0
	v_mov_b32_e32 v22, v0
	v_mov_b32_e32 v23, v0
	v_mov_b32_e32 v24, v0
	v_mov_b32_e32 v25, v0
	v_mov_b32_e32 v26, v0
	v_mov_b32_e32 v27, v0
	v_mov_b32_e32 v28, v0
	v_mov_b32_e32 v29, v0
	v_mov_b32_e32 v30, v0
	v_mov_b32_e32 v31, v0
	v_mov_b32_e32 v32, v0
	v_mov_b32_e32 v33, v0
	v_mov_b32_e32 v34, v0
	v_mov_b32_e32 v35, v0
	v_mov_b32_e32 v36, v0
	v_mov_b32_e32 v37, v0
	v_mov_b32_e32 v38, v0
	v_mov_b32_e32 v39, v0
	v_mov_b32_e32 v40, v0
	v_mov_b32_e32 v41, v0
	v_mov_b32_e32 v42, v0
	v_mov_b32_e32 v43, v0
	v_mov_b32_e32 v44, v0
	v_mov_b32_e32 v45, v0
	v_mov_b32_e32 v46, v0
	v_mov_b32_e32 v47, v0
	v_mov_b32_e32 v48, v0
	v_mov_b32_e32 v49, v0
	v_mov_b32_e32 v50, v0
	v_mov_b32_e32 v51, v0
	v_mov_b32_e32 v52, v0
	v_mov_b32_e32 v53, v0
	v_mov_b32_e32 v54, v0
	v_mov_b32_e32 v55, v0
	v_mov_b32_e32 v56, v0
	v_mov_b32_e32 v57, v0
	v_mov_b32_e32 v58, v0
	v_mov_b32_e32 v59, v0
	v_mov_b32_e32 v60, v0
	v_mov_b32_e32 v61, v0
	v_mov_b32_e32 v62, v0
	v_mov_b32_e32 v63, v0
	v_mov_b32_e32 v64, v0
	v_mov_b32_e32 v65, v0
	v_mov_b32_e32 v66, v0
	v_mov_b32_e32 v67, v0
	v_mov_b32_e32 v68, v0
	v_mov_b32_e32 v69, v0
	v_mov_b32_e32 v70, v0
	v_mov_b32_e32 v71, v0
	v_mov_b32_e32 v72, v0
	v_mov_b32_e32 v73, v0
	v_mov_b32_e32 v74, v0
	v_mov_b32_e32 v75, v0
	v_mov_b32_e32 v76, v0
	v_mov_b32_e32 v77, v0
	v_mov_b32_e32 v78, v0
	v_mov_b32_e32 v79, v0
	v_mov_b32_e32 v80, v0
	v_mov_b32_e32 v81, v0
	v_mov_b32_e32 v82, v0
	v_mov_b32_e32 v83, v0
	v_mov_b32_e32 v84, v0
	v_mov_b32_e32 v85, v0
	v_mov_b32_e32 v86, v0
	v_mov_b32_e32 v87, v0
	v_mov_b32_e32 v88, v0
	v_mov_b32_e32 v89, v0
	v_mov_b32_e32 v90, v0
	v_mov_b32_e32 v91, v0
	v_mov_b32_e32 v92, v0
	v_mov_b32_e32 v93, v0
	v_mov_b32_e32 v94, v0
	v_mov_b32_e32 v95, v0
	v_mov_b32_e32 v96, v0
	v_mov_b32_e32 v97, v0
	v_mov_b32_e32 v98, v0
	v_mov_b32_e32 v99, v0
	v_mov_b32_e32 v100, v0
	v_mov_b32_e32 v101, v0
	v_mov_b32_e32 v102, v0
	v_mov_b32_e32 v103, v0
	v_mov_b32_e32 v104, v0
	v_mov_b32_e32 v105, v0
	v_mov_b32_e32 v106, v0
	v_mov_b32_e32 v107, v0
	v_mov_b32_e32 v108, v0
	v_mov_b32_e32 v109, v0
	v_mov_b32_e32 v110, v0
	v_mov_b32_e32 v111, v0
	v_mov_b32_e32 v112, v0
	v_mov_b32_e32 v113, v0
	v_mov_b32_e32 v114, v0
	v_mov_b32_e32 v115, v0
	v_mov_b32_e32 v116, v0
	v_mov_b32_e32 v117, v0
	v_mov_b32_e32 v118, v0
	v_mov_b32_e32 v119, v0
	v_mov_b32_e32 v120, v0
	v_mov_b32_e32 v121, v0
	v_mov_b32_e32 v122, v0
	v_mov_b32_e32 v123, v0
	v_mov_b32_e32 v124, v0
	v_mov_b32_e32 v125, v0
	v_mov_b32_e32 v126, v0
	v_mov_b32_e32 v127, v0
	s_barrier
	.p2alignl 6, 3212836864
